# phase 0: nt (streaming) cache hint on the read-once f32 weight and x loads
# speedup vs baseline: 1.0105x; 1.0105x over previous
.LBB0_7:
	s_or_b64 exec, exec, s[0:1]
	v_readlane_b32 s0, v254, 2
	v_readlane_b32 s1, v254, 3
	s_cmpk_lg_i32 s1, 0xcfc7
	s_cbranch_scc1 .LBB0_19
	v_lshrrev_b32_e32 v1, 20, v0
	v_lshrrev_b32_e32 v0, 10, v0
	v_or_b32_e32 v0, v0, v1
	s_movk_i32 s0, 0x3ff
	v_and_or_b32 v0, v0, s0, v232
	v_cmp_eq_u32_e32 vcc, 0, v0
	s_barrier
	s_and_saveexec_b64 s[0:1], vcc
	s_cbranch_execz .LBB0_18
	buffer_wbl2 sc1
	s_waitcnt vmcnt(0)
	s_load_dwordx2 s[2:3], s[2:3], 0x58
	v_mov_b32_e32 v2, 0
	s_mov_b64 s[16:17], exec
	v_mbcnt_lo_u32_b32 v1, s16, 0
	v_mbcnt_hi_u32_b32 v1, s17, v1
	s_waitcnt lgkmcnt(0)
	global_load_dword v0, v2, s[2:3] offset:40 nt
	v_cmp_eq_u32_e32 vcc, 0, v1
	s_and_saveexec_b64 s[26:27], vcc
	s_cbranch_execz .LBB0_11
	s_bcnt1_i32_b64 s16, s[16:17]
	v_mov_b32_e32 v3, s16
	global_atomic_add v3, v2, v3, s[2:3] offset:32 sc0

.LBB0_21:
	v_lshl_add_u64 v[4:5], s[26:27], 2, v[24:25]
	global_load_dwordx4 v[0:3], v[4:5], off offset:16 nt
	s_nop 0
	global_load_dwordx4 v[4:7], v[4:5], off nt

.LBB0_24:
	s_cmpk_gt_i32 s90, 0x11ff
	s_mov_b64 s[16:17], -1
	s_cbranch_scc0 .LBB0_59
	s_cmpk_gt_u32 s90, 0x13ff
	s_cbranch_scc0 .LBB0_56
	s_cmpk_gt_u32 s90, 0x17ff
	s_cbranch_scc0 .LBB0_50
	s_cmpk_gt_u32 s90, 0x19ff
	s_cbranch_scc0 .LBB0_44
	s_cmpk_gt_u32 s90, 0x1bff
	s_cbranch_scc0 .LBB0_41
	s_cmpk_gt_u32 s90, 0x31ff
	s_cbranch_scc0 .LBB0_31
	s_add_i32 s6, s90, 0xffffce00
	s_add_i32 s16, s90, 0xffffc880
	s_cmpk_lt_u32 s6, 0x580
	s_cselect_b32 s16, s6, s16
	s_cmpk_gt_u32 s6, 0x57f
	s_cselect_b32 s6, 0xb00000, 0
	s_cselect_b32 s26, 0x580000, 0
	s_add_u32 s72, s24, s6
	s_addc_u32 s73, s25, 0
	s_lshl_b32 s6, s16, 1
	s_and_b32 s17, s6, 0xfc0
	s_lshl_b32 s6, s16, 5
	s_and_b32 s16, s6, 0x3e0
	v_or_b32_e32 v0, s17, v30
	s_add_u32 s26, s34, s26
	v_lshlrev_b32_e32 v0, 12, v0
	v_mov_b32_e32 v1, v9
	s_addc_u32 s27, s35, 0
	v_lshl_add_u64 v[0:1], s[72:73], 0, v[0:1]
	s_lshl_b32 s6, s16, 2
	v_lshl_add_u64 v[0:1], v[0:1], 0, s[6:7]
	v_lshl_add_u64 v[0:1], v[0:1], 0, v[8:9]
	s_movk_i32 s6, 0x2000
	v_add_co_u32_e32 v2, vcc, s6, v0
	s_movk_i32 s6, 0x4000
	s_nop 0
	v_addc_co_u32_e32 v3, vcc, 0, v1, vcc
	v_add_co_u32_e32 v4, vcc, s6, v0
	s_movk_i32 s6, 0x6000
	s_nop 0
	v_addc_co_u32_e32 v5, vcc, 0, v1, vcc
	v_add_co_u32_e32 v6, vcc, s6, v0
	s_mov_b32 s6, 0x8000
	s_nop 0
	v_addc_co_u32_e32 v7, vcc, 0, v1, vcc
	v_add_co_u32_e32 v44, vcc, s6, v0
	s_mov_b32 s6, 0xa000
	s_nop 0
	v_addc_co_u32_e32 v45, vcc, 0, v1, vcc
	v_add_co_u32_e32 v46, vcc, s6, v0
	s_mov_b32 s6, 0xc000
	s_nop 0
	v_addc_co_u32_e32 v47, vcc, 0, v1, vcc
	v_add_co_u32_e32 v48, vcc, s6, v0
	s_mov_b32 s6, 0xe000
	s_nop 0
	v_addc_co_u32_e32 v49, vcc, 0, v1, vcc
	v_add_co_u32_e32 v50, vcc, s6, v0
	s_mov_b32 s6, 0x10000
	s_nop 0
	v_addc_co_u32_e32 v51, vcc, 0, v1, vcc
	global_load_dword v27, v[0:1], off nt
	global_load_dword v54, v[2:3], off nt
	global_load_dword v55, v[4:5], off nt
	global_load_dword v56, v[6:7], off nt
	global_load_dword v57, v[44:45], off nt
	global_load_dword v58, v[46:47], off nt
	global_load_dword v59, v[48:49], off nt
	global_load_dword v60, v[50:51], off nt
	v_add_co_u32_e32 v2, vcc, s6, v0
	s_mov_b32 s6, 0x14000
	s_nop 0
	v_addc_co_u32_e32 v3, vcc, 0, v1, vcc
	v_add_co_u32_e32 v4, vcc, s42, v0
	v_readlane_b32 s72, v254, 10
	s_nop 0
	v_addc_co_u32_e32 v5, vcc, 0, v1, vcc
	v_add_co_u32_e32 v6, vcc, s6, v0
	s_mov_b32 s6, 0x18000
	s_nop 0
	v_addc_co_u32_e32 v7, vcc, 0, v1, vcc
	v_add_co_u32_e32 v44, vcc, s43, v0
	s_nop 1
	v_addc_co_u32_e32 v45, vcc, 0, v1, vcc
	v_add_co_u32_e32 v46, vcc, s6, v0
	s_mov_b32 s6, 0x1a000
	s_nop 0
	v_addc_co_u32_e32 v47, vcc, 0, v1, vcc
	v_add_co_u32_e32 v48, vcc, s6, v0
	s_mov_b32 s6, 0x1c000
	s_nop 0
	v_addc_co_u32_e32 v49, vcc, 0, v1, vcc
	v_add_co_u32_e32 v50, vcc, s6, v0
	s_mov_b32 s6, 0x1e000
	s_nop 0
	v_addc_co_u32_e32 v51, vcc, 0, v1, vcc
	v_add_co_u32_e32 v52, vcc, s6, v0
	s_mov_b32 s6, 0x20000
	s_nop 0
	v_addc_co_u32_e32 v53, vcc, 0, v1, vcc
	global_load_dword v61, v[2:3], off nt
	global_load_dword v62, v[4:5], off nt
	global_load_dword v63, v[6:7], off nt
	global_load_dword v64, v[44:45], off nt
	global_load_dword v65, v[46:47], off nt
	global_load_dword v66, v[48:49], off nt
	global_load_dword v67, v[50:51], off nt
	global_load_dword v68, v[52:53], off nt
	v_add_co_u32_e32 v2, vcc, s6, v0
	s_mov_b32 s6, 0x22000
	s_nop 0
	v_addc_co_u32_e32 v3, vcc, 0, v1, vcc
	v_add_co_u32_e32 v4, vcc, s6, v0
	s_mov_b32 s6, 0x26000
	s_nop 0
	v_addc_co_u32_e32 v5, vcc, 0, v1, vcc
	v_add_co_u32_e32 v6, vcc, s44, v0
	s_nop 1
	v_addc_co_u32_e32 v7, vcc, 0, v1, vcc
	v_add_co_u32_e32 v44, vcc, s6, v0
	s_mov_b32 s6, 0x28000
	s_nop 0
	v_addc_co_u32_e32 v45, vcc, 0, v1, vcc
	v_add_co_u32_e32 v46, vcc, s6, v0
	s_mov_b32 s6, 0x2a000
	s_nop 0
	v_addc_co_u32_e32 v47, vcc, 0, v1, vcc
	v_add_co_u32_e32 v48, vcc, s6, v0
	s_mov_b32 s6, 0x2e000
	s_nop 0
	v_addc_co_u32_e32 v49, vcc, 0, v1, vcc
	v_add_co_u32_e32 v50, vcc, s45, v0
	s_nop 1
	v_addc_co_u32_e32 v51, vcc, 0, v1, vcc
	v_add_co_u32_e32 v52, vcc, s6, v0
	s_mov_b32 s6, 0x30000
	s_nop 0
	v_addc_co_u32_e32 v53, vcc, 0, v1, vcc
	global_load_dword v69, v[2:3], off nt
	global_load_dword v70, v[4:5], off nt
	global_load_dword v71, v[6:7], off nt
	global_load_dword v72, v[44:45], off nt
	global_load_dword v73, v[46:47], off nt
	global_load_dword v74, v[48:49], off nt
	global_load_dword v75, v[50:51], off nt
	s_nop 0
	global_load_dword v52, v[52:53], off nt
	v_add_co_u32_e32 v2, vcc, s6, v0
	s_mov_b32 s6, 0x32000
	s_nop 0
	v_addc_co_u32_e32 v3, vcc, 0, v1, vcc
	v_add_co_u32_e32 v4, vcc, s6, v0
	s_mov_b32 s6, 0x34000
	s_nop 0
	v_addc_co_u32_e32 v5, vcc, 0, v1, vcc
	v_add_co_u32_e32 v6, vcc, s6, v0
	s_mov_b32 s6, 0x38000
	s_nop 0
	v_addc_co_u32_e32 v7, vcc, 0, v1, vcc
	v_add_co_u32_e32 v44, vcc, s46, v0
	s_nop 1
	v_addc_co_u32_e32 v45, vcc, 0, v1, vcc
	v_add_co_u32_e32 v46, vcc, s6, v0
	s_mov_b32 s6, 0x3a000
	s_nop 0
	v_addc_co_u32_e32 v47, vcc, 0, v1, vcc
	v_add_co_u32_e32 v48, vcc, s6, v0
	s_mov_b32 s6, 0x3c000
	s_nop 0
	v_addc_co_u32_e32 v49, vcc, 0, v1, vcc
	v_add_co_u32_e32 v50, vcc, s6, v0
	s_mov_b32 s6, 0x3e000
	s_nop 0
	v_addc_co_u32_e32 v51, vcc, 0, v1, vcc
	v_add_co_u32_e32 v0, vcc, s6, v0
	s_lshl_b32 s6, s17, 1
	s_nop 0
	v_addc_co_u32_e32 v1, vcc, 0, v1, vcc
	global_load_dword v2, v[2:3], off nt
	s_nop 0
	global_load_dword v3, v[4:5], off nt
	s_nop 0
	global_load_dword v4, v[6:7], off nt
	global_load_dword v5, v[44:45], off nt
	s_nop 0
	global_load_dword v6, v[46:47], off nt
	global_load_dword v7, v[48:49], off nt
	global_load_dword v44, v[50:51], off nt
	s_nop 0
	global_load_dword v0, v[0:1], off nt
	s_waitcnt vmcnt(16)
	s_waitcnt vmcnt(0)
	ds_write2_b32 v31, v27, v54 offset1:66
	ds_write2_b32 v31, v55, v56 offset0:132 offset1:198
	ds_write2_b32 v37, v57, v58 offset0:8 offset1:74
	ds_write2_b32 v37, v59, v60 offset0:140 offset1:206
	ds_write2_b32 v38, v61, v62 offset0:16 offset1:82
	ds_write2_b32 v38, v63, v64 offset0:148 offset1:214
	ds_write2_b32 v39, v65, v66 offset0:24 offset1:90
	ds_write2_b32 v39, v67, v68 offset0:156 offset1:222
	ds_write2_b32 v40, v69, v70 offset0:32 offset1:98
	ds_write2_b32 v40, v71, v72 offset0:164 offset1:230
	ds_write2_b32 v41, v73, v74 offset0:40 offset1:106
	ds_write2_b32 v41, v75, v52 offset0:172 offset1:238
	ds_write2_b32 v42, v2, v3 offset0:48 offset1:114
	ds_write2_b32 v42, v4, v5 offset0:180 offset1:246
	ds_write2_b32 v43, v6, v7 offset0:56 offset1:122
	ds_write2_b32 v43, v44, v0 offset0:188 offset1:254
	s_waitcnt lgkmcnt(0)
	ds_read2_b32 v[4:5], v33 offset0:33 offset1:41
	ds_read2_b32 v[6:7], v33 offset1:8
	ds_read2_b32 v[44:45], v33 offset0:66 offset1:74
	ds_read2_b32 v[46:47], v33 offset0:99 offset1:107
	ds_read2_b32 v[48:49], v33 offset0:132 offset1:140
	ds_read2_b32 v[50:51], v33 offset0:165 offset1:173
	ds_read2_b32 v[52:53], v33 offset0:198 offset1:206
	ds_read2_b32 v[54:55], v33 offset0:231 offset1:239
	s_add_u32 s26, s26, s6
	s_waitcnt lgkmcnt(6)
	v_cvt_pk_bf16_f32 v0, v6, v4
	v_or_b32_e32 v4, s16, v32
	s_addc_u32 s27, s27, 0
	v_mov_b32_e32 v27, v9
	v_mul_u32_u24_e32 v4, 0xb00, v4
	v_lshl_add_u64 v[56:57], s[26:27], 0, v[26:27]
	v_lshlrev_b32_e32 v58, 1, v4
	v_mov_b32_e32 v59, v9
	s_waitcnt lgkmcnt(4)
	v_cvt_pk_bf16_f32 v1, v44, v46
	s_waitcnt lgkmcnt(2)
	v_cvt_pk_bf16_f32 v2, v48, v50
	s_waitcnt lgkmcnt(0)
	v_cvt_pk_bf16_f32 v3, v52, v54
	v_lshl_add_u64 v[58:59], v[56:57], 0, v[58:59]
	v_or_b32_e32 v4, s16, v34
	global_store_dwordx4 v[58:59], v[0:3], off
	v_mul_u32_u24_e32 v4, 0xb00, v4
	v_lshlrev_b32_e32 v4, 1, v4
	v_cvt_pk_bf16_f32 v0, v7, v5
	v_cvt_pk_bf16_f32 v1, v45, v47
	v_cvt_pk_bf16_f32 v2, v49, v51
	v_cvt_pk_bf16_f32 v3, v53, v55
	v_mov_b32_e32 v5, v9
	ds_read2_b32 v[6:7], v33 offset0:16 offset1:24
	ds_read2_b32 v[44:45], v33 offset0:49 offset1:57
	ds_read2_b32 v[46:47], v33 offset0:82 offset1:90
	ds_read2_b32 v[48:49], v33 offset0:115 offset1:123
	ds_read2_b32 v[50:51], v33 offset0:148 offset1:156
	ds_read2_b32 v[52:53], v33 offset0:181 offset1:189
	ds_read2_b32 v[54:55], v33 offset0:214 offset1:222
	ds_read2_b32 v[58:59], v33 offset0:247 offset1:255
	v_lshl_add_u64 v[4:5], v[56:57], 0, v[4:5]
	global_store_dwordx4 v[4:5], v[0:3], off
	v_or_b32_e32 v4, s16, v35
	v_mul_u32_u24_e32 v4, 0xb00, v4
	v_lshlrev_b32_e32 v4, 1, v4
	v_mov_b32_e32 v5, v9
	s_waitcnt lgkmcnt(6)
	v_cvt_pk_bf16_f32 v0, v6, v44
	s_waitcnt lgkmcnt(4)
	v_cvt_pk_bf16_f32 v1, v46, v48
	s_waitcnt lgkmcnt(2)
	v_cvt_pk_bf16_f32 v2, v50, v52
	s_waitcnt lgkmcnt(0)
	v_cvt_pk_bf16_f32 v3, v54, v58
	v_lshl_add_u64 v[4:5], v[56:57], 0, v[4:5]
	global_store_dwordx4 v[4:5], v[0:3], off
	v_or_b32_e32 v4, s16, v36
	v_mul_u32_u24_e32 v4, 0xb00, v4
	v_lshlrev_b32_e32 v4, 1, v4
	v_mov_b32_e32 v5, v9
	v_cvt_pk_bf16_f32 v0, v7, v45
	v_cvt_pk_bf16_f32 v1, v47, v49
	v_cvt_pk_bf16_f32 v2, v51, v53
	v_cvt_pk_bf16_f32 v3, v55, v59
	v_lshl_add_u64 v[4:5], v[56:57], 0, v[4:5]
	global_store_dwordx4 v[4:5], v[0:3], off
	s_waitcnt lgkmcnt(0)
	s_mov_b64 s[16:17], 0

.LBB0_36:
	s_cmpk_gt_u32 s27, 0xaff
	s_cselect_b64 s[16:17], -1, 0
	s_and_b64 s[92:93], s[16:17], exec
	s_cselect_b32 s27, 0x1600000, 0
	s_add_u32 s92, s22, s27
	s_addc_u32 s93, s23, 0
	s_lshl_b32 s73, s26, 6
	v_or_b32_e32 v2, s73, v30
	v_mov_b64_e32 v[0:1], s[92:93]
	s_movk_i32 s26, 0x5800
	v_mad_u64_u32 v[0:1], s[26:27], v2, s26, v[0:1]
	v_lshl_add_u64 v[0:1], s[6:7], 2, v[0:1]
	v_lshl_add_u64 v[0:1], v[0:1], 0, v[8:9]
	s_mov_b32 s6, 0xb000
	v_add_co_u32_e32 v2, vcc, s6, v0
	s_mov_b32 s6, 0x21000
	s_nop 0
	v_addc_co_u32_e32 v3, vcc, 0, v1, vcc
	v_add_co_u32_e32 v4, vcc, s43, v0
	s_and_b64 s[26:27], s[16:17], exec
	s_nop 0
	v_addc_co_u32_e32 v5, vcc, 0, v1, vcc
	v_add_co_u32_e32 v6, vcc, s6, v0
	s_mov_b32 s6, 0x37000
	s_nop 0
	v_addc_co_u32_e32 v7, vcc, 0, v1, vcc
	v_add_co_u32_e32 v48, vcc, s45, v0
	s_nop 1
	v_addc_co_u32_e32 v49, vcc, 0, v1, vcc
	v_add_co_u32_e32 v50, vcc, s6, v0
	s_mov_b32 s6, 0x42000
	s_nop 0
	v_addc_co_u32_e32 v51, vcc, 0, v1, vcc
	v_add_co_u32_e32 v52, vcc, s6, v0
	s_mov_b32 s6, 0x4d000
	s_nop 0
	v_addc_co_u32_e32 v53, vcc, 0, v1, vcc
	v_add_co_u32_e32 v54, vcc, s6, v0
	s_mov_b32 s6, 0x58000
	s_nop 0
	v_addc_co_u32_e32 v55, vcc, 0, v1, vcc
	global_load_dword v27, v[0:1], off nt
	global_load_dword v44, v[2:3], off nt
	global_load_dword v45, v[4:5], off nt
	global_load_dword v46, v[6:7], off nt
	global_load_dword v47, v[48:49], off nt
	s_nop 0
	global_load_dword v48, v[50:51], off nt
	global_load_dword v49, v[52:53], off nt
	s_nop 0
	global_load_dword v50, v[54:55], off nt
	v_add_co_u32_e32 v2, vcc, s6, v0
	s_mov_b32 s6, 0x63000
	s_nop 0
	v_addc_co_u32_e32 v3, vcc, 0, v1, vcc
	v_add_co_u32_e32 v4, vcc, s6, v0
	s_mov_b32 s6, 0x79000
	s_nop 0
	v_addc_co_u32_e32 v5, vcc, 0, v1, vcc
	v_add_co_u32_e32 v6, vcc, s47, v0
	s_nop 1
	v_addc_co_u32_e32 v7, vcc, 0, v1, vcc
	v_add_co_u32_e32 v54, vcc, s6, v0
	s_mov_b32 s6, 0x8f000
	s_nop 0
	v_addc_co_u32_e32 v55, vcc, 0, v1, vcc
	v_add_co_u32_e32 v56, vcc, s48, v0
	s_nop 1
	v_addc_co_u32_e32 v57, vcc, 0, v1, vcc
	v_add_co_u32_e32 v58, vcc, s6, v0
	s_mov_b32 s6, 0x9a000
	s_nop 0
	v_addc_co_u32_e32 v59, vcc, 0, v1, vcc
	v_add_co_u32_e32 v60, vcc, s6, v0
	s_mov_b32 s6, 0xa5000
	s_nop 0
	v_addc_co_u32_e32 v61, vcc, 0, v1, vcc
	v_add_co_u32_e32 v62, vcc, s6, v0
	s_mov_b32 s6, 0xb0000
	s_nop 0
	v_addc_co_u32_e32 v63, vcc, 0, v1, vcc
	global_load_dword v51, v[2:3], off nt
	global_load_dword v52, v[4:5], off nt
	global_load_dword v53, v[6:7], off nt
	s_nop 0
	global_load_dword v54, v[54:55], off nt
	s_nop 0
	global_load_dword v55, v[56:57], off nt
	s_nop 0
	global_load_dword v56, v[58:59], off nt
	global_load_dword v57, v[60:61], off nt
	s_nop 0
	global_load_dword v58, v[62:63], off nt
	v_add_co_u32_e32 v2, vcc, s6, v0
	s_cselect_b32 s6, 0x1000, 0
	s_nop 0
	v_addc_co_u32_e32 v3, vcc, 0, v1, vcc
	v_add_co_u32_e32 v4, vcc, s49, v0
	s_add_u32 s26, s20, s6
	s_nop 0
	v_addc_co_u32_e32 v5, vcc, 0, v1, vcc
	v_add_co_u32_e32 v6, vcc, s50, v0
	s_addc_u32 s27, s21, 0
	s_nop 0
	v_addc_co_u32_e32 v7, vcc, 0, v1, vcc
	v_add_co_u32_e32 v62, vcc, s51, v0
	s_cmp_eq_u64 s[26:27], 0
	s_nop 0
	v_addc_co_u32_e32 v63, vcc, 0, v1, vcc
	v_add_co_u32_e32 v64, vcc, s52, v0
	s_mov_b32 s6, s73
	s_nop 0
	v_addc_co_u32_e32 v65, vcc, 0, v1, vcc
	v_add_co_u32_e32 v66, vcc, s53, v0
	s_nop 1
	v_addc_co_u32_e32 v67, vcc, 0, v1, vcc
	v_add_co_u32_e32 v68, vcc, s54, v0
	s_nop 1
	v_addc_co_u32_e32 v69, vcc, 0, v1, vcc
	v_add_co_u32_e32 v70, vcc, s55, v0
	s_nop 1
	v_addc_co_u32_e32 v71, vcc, 0, v1, vcc
	global_load_dword v59, v[2:3], off nt
	global_load_dword v60, v[4:5], off nt
	global_load_dword v61, v[6:7], off nt
	s_nop 0
	global_load_dword v62, v[62:63], off nt
	s_nop 0
	global_load_dword v63, v[64:65], off nt
	s_nop 0
	global_load_dword v64, v[66:67], off nt
	global_load_dword v65, v[68:69], off nt
	s_nop 0
	global_load_dword v66, v[70:71], off nt
	v_add_co_u32_e32 v2, vcc, s56, v0
	s_nop 1
	v_addc_co_u32_e32 v3, vcc, 0, v1, vcc
	v_add_co_u32_e32 v4, vcc, s57, v0
	s_nop 1
	v_addc_co_u32_e32 v5, vcc, 0, v1, vcc
	v_add_co_u32_e32 v6, vcc, s58, v0
	s_nop 1
	v_addc_co_u32_e32 v7, vcc, 0, v1, vcc
	v_add_co_u32_e32 v70, vcc, s59, v0
	s_nop 1
	v_addc_co_u32_e32 v71, vcc, 0, v1, vcc
	v_add_co_u32_e32 v72, vcc, s60, v0
	s_nop 1
	v_addc_co_u32_e32 v73, vcc, 0, v1, vcc
	v_add_co_u32_e32 v74, vcc, 0x13f000, v0
	s_nop 1
	v_addc_co_u32_e32 v75, vcc, 0, v1, vcc
	v_add_co_u32_e32 v76, vcc, 0x14a000, v0
	s_nop 1
	v_addc_co_u32_e32 v77, vcc, 0, v1, vcc
	v_add_co_u32_e32 v0, vcc, 0x155000, v0
	s_nop 1
	v_addc_co_u32_e32 v1, vcc, 0, v1, vcc
	global_load_dword v67, v[2:3], off nt
	global_load_dword v68, v[4:5], off nt
	global_load_dword v69, v[6:7], off nt
	s_nop 0
	global_load_dword v70, v[70:71], off nt
	s_nop 0
	global_load_dword v71, v[72:73], off nt
	s_nop 0
	global_load_dword v72, v[74:75], off nt
	global_load_dword v73, v[76:77], off nt
	s_nop 0
	global_load_dword v74, v[0:1], off nt
	s_cbranch_scc1 .LBB0_38
	s_lshl_b64 s[92:93], s[6:7], 2
	s_add_u32 s26, s26, s92
	s_addc_u32 s27, s27, s93
	v_lshlrev_b32_e32 v4, 2, v10
	global_load_dwordx4 v[0:3], v4, s[26:27] offset:16 nt
	s_nop 0
	global_load_dwordx4 v[4:7], v4, s[26:27] nt
	s_branch .LBB0_39

.LBB0_41:
	s_andn2_b64 vcc, exec, s[16:17]
	s_cbranch_vccnz .LBB0_43
	s_and_b32 s6, s40, 0x3fc0
	s_add_i32 s16, s6, 0xffffcc00
	v_or_b32_e32 v0, s16, v30
	v_mov_b32_e32 v1, v9
	s_and_b32 s26, s38, 0x3e0
	v_lshlrev_b64 v[0:1], 12, v[0:1]
	v_lshl_add_u64 v[0:1], s[18:19], 0, v[0:1]
	s_lshl_b32 s6, s26, 2
	v_lshl_add_u64 v[0:1], v[0:1], 0, s[6:7]
	v_lshl_add_u64 v[0:1], v[0:1], 0, v[8:9]
	v_add_co_u32_e32 v2, vcc, 0x2000, v0
	s_mov_b32 s17, s7
	s_nop 0
	v_addc_co_u32_e32 v3, vcc, 0, v1, vcc
	v_add_co_u32_e32 v4, vcc, 0x4000, v0
	s_nop 1
	v_addc_co_u32_e32 v5, vcc, 0, v1, vcc
	v_add_co_u32_e32 v6, vcc, 0x6000, v0
	s_nop 1
	v_addc_co_u32_e32 v7, vcc, 0, v1, vcc
	v_add_co_u32_e32 v44, vcc, 0x8000, v0
	s_nop 1
	v_addc_co_u32_e32 v45, vcc, 0, v1, vcc
	v_add_co_u32_e32 v46, vcc, 0xa000, v0
	s_nop 1
	v_addc_co_u32_e32 v47, vcc, 0, v1, vcc
	v_add_co_u32_e32 v48, vcc, 0xc000, v0
	s_nop 1
	v_addc_co_u32_e32 v49, vcc, 0, v1, vcc
	v_add_co_u32_e32 v50, vcc, 0xe000, v0
	s_nop 1
	v_addc_co_u32_e32 v51, vcc, 0, v1, vcc
	global_load_dword v27, v[0:1], off nt
	global_load_dword v54, v[2:3], off nt
	global_load_dword v55, v[4:5], off nt
	global_load_dword v56, v[6:7], off nt
	global_load_dword v57, v[44:45], off nt
	global_load_dword v58, v[46:47], off nt
	global_load_dword v59, v[48:49], off nt
	global_load_dword v60, v[50:51], off nt
	v_add_co_u32_e32 v2, vcc, 0x10000, v0
	s_nop 1
	v_addc_co_u32_e32 v3, vcc, 0, v1, vcc
	v_add_co_u32_e32 v4, vcc, 0x12000, v0
	s_nop 1
	v_addc_co_u32_e32 v5, vcc, 0, v1, vcc
	v_add_co_u32_e32 v6, vcc, 0x14000, v0
	s_nop 1
	v_addc_co_u32_e32 v7, vcc, 0, v1, vcc
	v_add_co_u32_e32 v44, vcc, 0x16000, v0
	s_nop 1
	v_addc_co_u32_e32 v45, vcc, 0, v1, vcc
	v_add_co_u32_e32 v46, vcc, 0x18000, v0
	s_nop 1
	v_addc_co_u32_e32 v47, vcc, 0, v1, vcc
	v_add_co_u32_e32 v48, vcc, 0x1a000, v0
	s_nop 1
	v_addc_co_u32_e32 v49, vcc, 0, v1, vcc
	v_add_co_u32_e32 v50, vcc, 0x1c000, v0
	s_nop 1
	v_addc_co_u32_e32 v51, vcc, 0, v1, vcc
	v_add_co_u32_e32 v52, vcc, 0x1e000, v0
	s_nop 1
	v_addc_co_u32_e32 v53, vcc, 0, v1, vcc
	global_load_dword v61, v[2:3], off nt
	global_load_dword v62, v[4:5], off nt
	global_load_dword v63, v[6:7], off nt
	global_load_dword v64, v[44:45], off nt
	global_load_dword v65, v[46:47], off nt
	global_load_dword v66, v[48:49], off nt
	global_load_dword v67, v[50:51], off nt
	global_load_dword v68, v[52:53], off nt
	v_add_co_u32_e32 v2, vcc, 0x20000, v0
	s_nop 1
	v_addc_co_u32_e32 v3, vcc, 0, v1, vcc
	v_add_co_u32_e32 v4, vcc, 0x22000, v0
	s_nop 1
	v_addc_co_u32_e32 v5, vcc, 0, v1, vcc
	v_add_co_u32_e32 v6, vcc, 0x24000, v0
	s_nop 1
	v_addc_co_u32_e32 v7, vcc, 0, v1, vcc
	v_add_co_u32_e32 v44, vcc, 0x26000, v0
	s_nop 1
	v_addc_co_u32_e32 v45, vcc, 0, v1, vcc
	v_add_co_u32_e32 v46, vcc, 0x28000, v0
	s_nop 1
	v_addc_co_u32_e32 v47, vcc, 0, v1, vcc
	v_add_co_u32_e32 v48, vcc, 0x2a000, v0
	s_nop 1
	v_addc_co_u32_e32 v49, vcc, 0, v1, vcc
	v_add_co_u32_e32 v50, vcc, 0x2c000, v0
	s_nop 1
	v_addc_co_u32_e32 v51, vcc, 0, v1, vcc
	v_add_co_u32_e32 v52, vcc, 0x2e000, v0
	s_nop 1
	v_addc_co_u32_e32 v53, vcc, 0, v1, vcc
	global_load_dword v69, v[2:3], off nt
	global_load_dword v70, v[4:5], off nt
	global_load_dword v71, v[6:7], off nt
	global_load_dword v72, v[44:45], off nt
	global_load_dword v73, v[46:47], off nt
	global_load_dword v74, v[48:49], off nt
	global_load_dword v75, v[50:51], off nt
	s_nop 0
	global_load_dword v52, v[52:53], off nt
	v_add_co_u32_e32 v2, vcc, 0x30000, v0
	s_nop 1
	v_addc_co_u32_e32 v3, vcc, 0, v1, vcc
	v_add_co_u32_e32 v4, vcc, 0x32000, v0
	s_nop 1
	v_addc_co_u32_e32 v5, vcc, 0, v1, vcc
	v_add_co_u32_e32 v6, vcc, 0x34000, v0
	s_nop 1
	v_addc_co_u32_e32 v7, vcc, 0, v1, vcc
	v_add_co_u32_e32 v44, vcc, 0x36000, v0
	s_nop 1
	v_addc_co_u32_e32 v45, vcc, 0, v1, vcc
	v_add_co_u32_e32 v46, vcc, 0x38000, v0
	s_nop 1
	v_addc_co_u32_e32 v47, vcc, 0, v1, vcc
	v_add_co_u32_e32 v48, vcc, 0x3a000, v0
	s_nop 1
	v_addc_co_u32_e32 v49, vcc, 0, v1, vcc
	v_add_co_u32_e32 v50, vcc, 0x3c000, v0
	s_nop 1
	v_addc_co_u32_e32 v51, vcc, 0, v1, vcc
	v_add_co_u32_e32 v0, vcc, 0x3e000, v0
	s_nop 1
	v_addc_co_u32_e32 v1, vcc, 0, v1, vcc
	global_load_dword v2, v[2:3], off nt
	s_nop 0
	global_load_dword v3, v[4:5], off nt
	s_nop 0
	global_load_dword v4, v[6:7], off nt
	global_load_dword v5, v[44:45], off nt
	s_nop 0
	global_load_dword v6, v[46:47], off nt
	global_load_dword v7, v[48:49], off nt
	global_load_dword v44, v[50:51], off nt
	s_nop 0
	global_load_dword v0, v[0:1], off nt
	s_waitcnt vmcnt(16)
	s_waitcnt vmcnt(0)
	ds_write2_b32 v31, v27, v54 offset1:66
	ds_write2_b32 v31, v55, v56 offset0:132 offset1:198
	ds_write2_b32 v37, v57, v58 offset0:8 offset1:74
	ds_write2_b32 v37, v59, v60 offset0:140 offset1:206
	ds_write2_b32 v38, v61, v62 offset0:16 offset1:82
	ds_write2_b32 v38, v63, v64 offset0:148 offset1:214
	ds_write2_b32 v39, v65, v66 offset0:24 offset1:90
	ds_write2_b32 v39, v67, v68 offset0:156 offset1:222
	ds_write2_b32 v40, v69, v70 offset0:32 offset1:98
	ds_write2_b32 v40, v71, v72 offset0:164 offset1:230
	ds_write2_b32 v41, v73, v74 offset0:40 offset1:106
	ds_write2_b32 v41, v75, v52 offset0:172 offset1:238
	ds_write2_b32 v42, v2, v3 offset0:48 offset1:114
	ds_write2_b32 v42, v4, v5 offset0:180 offset1:246
	ds_write2_b32 v43, v6, v7 offset0:56 offset1:122
	ds_write2_b32 v43, v44, v0 offset0:188 offset1:254
	s_waitcnt lgkmcnt(0)
	ds_read2_b32 v[4:5], v33 offset0:33 offset1:41
	ds_read2_b32 v[6:7], v33 offset1:8
	ds_read2_b32 v[44:45], v33 offset0:66 offset1:74
	ds_read2_b32 v[46:47], v33 offset0:99 offset1:107
	ds_read2_b32 v[48:49], v33 offset0:132 offset1:140
	ds_read2_b32 v[50:51], v33 offset0:165 offset1:173
	ds_read2_b32 v[52:53], v33 offset0:198 offset1:206
	ds_read2_b32 v[54:55], v33 offset0:231 offset1:239
	s_waitcnt lgkmcnt(6)
	v_cvt_pk_bf16_f32 v0, v6, v4
	v_or_b32_e32 v4, s26, v32
	v_lshl_add_u64 v[56:57], s[16:17], 1, v[12:13]
	v_lshlrev_b32_e32 v58, 11, v4
	v_mov_b32_e32 v59, v9
	s_waitcnt lgkmcnt(4)
	v_cvt_pk_bf16_f32 v1, v44, v46
	s_waitcnt lgkmcnt(2)
	v_cvt_pk_bf16_f32 v2, v48, v50
	s_waitcnt lgkmcnt(0)
	v_cvt_pk_bf16_f32 v3, v52, v54
	v_lshl_add_u64 v[58:59], v[56:57], 0, v[58:59]
	global_store_dwordx4 v[58:59], v[0:3], off
	v_or_b32_e32 v4, s26, v34
	v_lshlrev_b32_e32 v4, 11, v4
	v_cvt_pk_bf16_f32 v0, v7, v5
	v_cvt_pk_bf16_f32 v1, v45, v47
	v_cvt_pk_bf16_f32 v2, v49, v51
	v_cvt_pk_bf16_f32 v3, v53, v55
	ds_read2_b32 v[6:7], v33 offset0:49 offset1:57
	ds_read2_b32 v[44:45], v33 offset0:16 offset1:24
	ds_read2_b32 v[46:47], v33 offset0:82 offset1:90
	ds_read2_b32 v[48:49], v33 offset0:115 offset1:123
	ds_read2_b32 v[50:51], v33 offset0:148 offset1:156
	ds_read2_b32 v[52:53], v33 offset0:181 offset1:189
	ds_read2_b32 v[54:55], v33 offset0:214 offset1:222
	ds_read2_b32 v[58:59], v33 offset0:247 offset1:255
	v_mov_b32_e32 v5, v9
	v_lshl_add_u64 v[4:5], v[56:57], 0, v[4:5]
	global_store_dwordx4 v[4:5], v[0:3], off
	v_or_b32_e32 v4, s26, v35
	v_lshlrev_b32_e32 v4, 11, v4
	v_mov_b32_e32 v5, v9
	s_waitcnt lgkmcnt(6)
	v_cvt_pk_bf16_f32 v0, v44, v6
	s_waitcnt lgkmcnt(4)
	v_cvt_pk_bf16_f32 v1, v46, v48
	s_waitcnt lgkmcnt(2)
	v_cvt_pk_bf16_f32 v2, v50, v52
	s_waitcnt lgkmcnt(0)
	v_cvt_pk_bf16_f32 v3, v54, v58
	v_lshl_add_u64 v[4:5], v[56:57], 0, v[4:5]
	global_store_dwordx4 v[4:5], v[0:3], off
	v_or_b32_e32 v4, s26, v36
	v_lshlrev_b32_e32 v4, 11, v4
	v_mov_b32_e32 v5, v9
	v_cvt_pk_bf16_f32 v0, v45, v7
	v_cvt_pk_bf16_f32 v1, v47, v49
	v_cvt_pk_bf16_f32 v2, v51, v53
	v_cvt_pk_bf16_f32 v3, v55, v59
	v_lshl_add_u64 v[4:5], v[56:57], 0, v[4:5]
	global_store_dwordx4 v[4:5], v[0:3], off
	s_waitcnt lgkmcnt(0)

.LBB0_44:
	s_andn2_b64 vcc, exec, s[16:17]
	s_cbranch_vccnz .LBB0_49
	s_and_b32 s17, s40, 0x3fc0
	s_addk_i32 s17, 0xd000
	s_and_b32 s16, s38, 0x3e0
	v_or_b32_e32 v2, s17, v30
	v_mov_b64_e32 v[0:1], s[14:15]
	v_mad_u64_u32 v[0:1], s[26:27], v2, s61, v[0:1]
	s_lshl_b32 s6, s16, 2
	v_lshl_add_u64 v[0:1], v[0:1], 0, s[6:7]
	v_lshl_add_u64 v[0:1], v[0:1], 0, v[8:9]
	v_add_co_u32_e32 v2, vcc, 0x2000, v0
	s_mov_b32 s6, s17
	s_nop 0
	v_addc_co_u32_e32 v3, vcc, 0, v1, vcc
	v_add_co_u32_e32 v4, vcc, 0x8000, v0
	s_nop 1
	v_addc_co_u32_e32 v5, vcc, 0, v1, vcc
	v_add_co_u32_e32 v6, vcc, 0xe000, v0
	s_nop 1
	v_addc_co_u32_e32 v7, vcc, 0, v1, vcc
	v_add_co_u32_e32 v46, vcc, 0x14000, v0
	s_nop 1
	v_addc_co_u32_e32 v47, vcc, 0, v1, vcc
	v_add_co_u32_e32 v48, vcc, 0x1a000, v0
	s_nop 1
	v_addc_co_u32_e32 v49, vcc, 0, v1, vcc
	v_add_co_u32_e32 v50, vcc, 0x20000, v0
	s_nop 1
	v_addc_co_u32_e32 v51, vcc, 0, v1, vcc
	v_add_co_u32_e32 v52, vcc, 0x26000, v0
	s_nop 1
	v_addc_co_u32_e32 v53, vcc, 0, v1, vcc
	v_add_co_u32_e32 v54, vcc, 0x2c000, v0
	s_nop 1
	v_addc_co_u32_e32 v55, vcc, 0, v1, vcc
	global_load_dword v27, v[2:3], off nt
	global_load_dword v44, v[4:5], off offset:128 nt
	global_load_dword v45, v[6:7], off offset:256 nt
	s_nop 0
	global_load_dword v46, v[46:47], off offset:384 nt
	s_nop 0
	global_load_dword v47, v[48:49], off offset:512 nt
	s_nop 0
	global_load_dword v48, v[50:51], off offset:640 nt
	global_load_dword v49, v[52:53], off offset:768 nt
	s_nop 0
	global_load_dword v50, v[54:55], off offset:896 nt
	v_add_co_u32_e32 v2, vcc, 0x32000, v0
	s_nop 1
	v_addc_co_u32_e32 v3, vcc, 0, v1, vcc
	v_add_co_u32_e32 v4, vcc, 0x38000, v0
	s_nop 1
	v_addc_co_u32_e32 v5, vcc, 0, v1, vcc
	v_add_co_u32_e32 v6, vcc, 0x3e000, v0
	s_nop 1
	v_addc_co_u32_e32 v7, vcc, 0, v1, vcc
	v_add_co_u32_e32 v54, vcc, 0x44000, v0
	s_nop 1
	v_addc_co_u32_e32 v55, vcc, 0, v1, vcc
	v_add_co_u32_e32 v56, vcc, 0x4a000, v0
	s_nop 1
	v_addc_co_u32_e32 v57, vcc, 0, v1, vcc
	v_add_co_u32_e32 v58, vcc, 0x50000, v0
	s_nop 1
	v_addc_co_u32_e32 v59, vcc, 0, v1, vcc
	v_add_co_u32_e32 v60, vcc, 0x56000, v0
	s_nop 1
	v_addc_co_u32_e32 v61, vcc, 0, v1, vcc
	v_add_co_u32_e32 v62, vcc, 0x5c000, v0
	s_nop 1
	v_addc_co_u32_e32 v63, vcc, 0, v1, vcc
	global_load_dword v51, v[2:3], off offset:1024 nt
	global_load_dword v52, v[4:5], off offset:1152 nt
	global_load_dword v53, v[6:7], off offset:1280 nt
	s_nop 0
	global_load_dword v54, v[54:55], off offset:1408 nt
	s_nop 0
	global_load_dword v55, v[56:57], off offset:1536 nt
	s_nop 0
	global_load_dword v56, v[58:59], off offset:1664 nt
	global_load_dword v57, v[60:61], off offset:1792 nt
	s_nop 0
	global_load_dword v58, v[62:63], off offset:1920 nt
	v_add_co_u32_e32 v2, vcc, 0x62000, v0
	s_nop 1
	v_addc_co_u32_e32 v3, vcc, 0, v1, vcc
	v_add_co_u32_e32 v4, vcc, 0x68000, v0
	s_nop 1
	v_addc_co_u32_e32 v5, vcc, 0, v1, vcc
	v_add_co_u32_e32 v6, vcc, s47, v0
	s_nop 1
	v_addc_co_u32_e32 v7, vcc, 0, v1, vcc
	v_add_co_u32_e32 v62, vcc, 0x74000, v0
	s_nop 1
	v_addc_co_u32_e32 v63, vcc, 0, v1, vcc
	v_add_co_u32_e32 v64, vcc, 0x7a000, v0
	s_nop 1
	v_addc_co_u32_e32 v65, vcc, 0, v1, vcc
	v_add_co_u32_e32 v66, vcc, 0x80000, v0
	s_nop 1
	v_addc_co_u32_e32 v67, vcc, 0, v1, vcc
	v_add_co_u32_e32 v68, vcc, 0x86000, v0
	s_nop 1
	v_addc_co_u32_e32 v69, vcc, 0, v1, vcc
	v_add_co_u32_e32 v70, vcc, 0x8c000, v0
	s_nop 1
	v_addc_co_u32_e32 v71, vcc, 0, v1, vcc
	global_load_dword v59, v[2:3], off offset:2048 nt
	global_load_dword v60, v[4:5], off offset:2176 nt
	global_load_dword v61, v[6:7], off offset:2304 nt
	s_nop 0
	global_load_dword v62, v[62:63], off offset:2432 nt
	s_nop 0
	global_load_dword v63, v[64:65], off offset:2560 nt
	s_nop 0
	global_load_dword v64, v[66:67], off offset:2688 nt
	global_load_dword v65, v[68:69], off offset:2816 nt
	s_nop 0
	global_load_dword v66, v[70:71], off offset:2944 nt
	v_add_co_u32_e32 v2, vcc, 0x92000, v0
	s_nop 1
	v_addc_co_u32_e32 v3, vcc, 0, v1, vcc
	v_add_co_u32_e32 v4, vcc, 0x98000, v0
	s_nop 1
	v_addc_co_u32_e32 v5, vcc, 0, v1, vcc
	v_add_co_u32_e32 v6, vcc, 0x9e000, v0
	s_nop 1
	v_addc_co_u32_e32 v7, vcc, 0, v1, vcc
	v_add_co_u32_e32 v70, vcc, 0xa4000, v0
	s_nop 1
	v_addc_co_u32_e32 v71, vcc, 0, v1, vcc
	v_add_co_u32_e32 v72, vcc, 0xaa000, v0
	s_nop 1
	v_addc_co_u32_e32 v73, vcc, 0, v1, vcc
	v_add_co_u32_e32 v74, vcc, 0xb0000, v0
	s_nop 1
	v_addc_co_u32_e32 v75, vcc, 0, v1, vcc
	v_add_co_u32_e32 v76, vcc, 0xb6000, v0
	s_nop 1
	v_addc_co_u32_e32 v77, vcc, 0, v1, vcc
	v_add_co_u32_e32 v0, vcc, 0xbc000, v0
	s_nop 1
	v_addc_co_u32_e32 v1, vcc, 0, v1, vcc
	global_load_dword v67, v[2:3], off offset:3072 nt
	global_load_dword v68, v[4:5], off offset:3200 nt
	global_load_dword v69, v[6:7], off offset:3328 nt
	s_nop 0
	global_load_dword v70, v[70:71], off offset:3456 nt
	s_nop 0
	global_load_dword v71, v[72:73], off offset:3584 nt
	s_nop 0
	global_load_dword v72, v[74:75], off offset:3712 nt
	global_load_dword v73, v[76:77], off offset:3840 nt
	s_nop 0
	global_load_dword v74, v[0:1], off offset:3968 nt
	s_andn2_b64 vcc, exec, s[0:1]
	s_cbranch_vccnz .LBB0_47
	v_lshl_add_u64 v[4:5], s[6:7], 2, v[22:23]
	global_load_dwordx4 v[0:3], v[4:5], off offset:16 nt
	s_nop 0
	global_load_dwordx4 v[4:7], v[4:5], off nt
	s_branch .LBB0_48

.LBB0_50:
	s_andn2_b64 vcc, exec, s[16:17]
	s_cbranch_vccnz .LBB0_55
	s_and_b32 s17, s90, 0x1fc0
	s_addk_i32 s17, 0xec00
	s_and_b32 s16, s38, 0x7e0
	v_or_b32_e32 v2, s17, v30
	v_mov_b64_e32 v[0:1], s[14:15]
	v_mad_u64_u32 v[0:1], s[26:27], v2, s61, v[0:1]
	s_lshl_b32 s6, s16, 2
	v_lshl_add_u64 v[0:1], v[0:1], 0, s[6:7]
	v_lshl_add_u64 v[0:1], v[0:1], 0, v[8:9]
	v_add_co_u32_e32 v2, vcc, 0x6000, v0
	s_mov_b32 s6, s17
	s_nop 0
	v_addc_co_u32_e32 v3, vcc, 0, v1, vcc
	v_add_co_u32_e32 v4, vcc, 0xc000, v0
	s_nop 1
	v_addc_co_u32_e32 v5, vcc, 0, v1, vcc
	v_add_co_u32_e32 v6, vcc, 0x12000, v0
	s_nop 1
	v_addc_co_u32_e32 v7, vcc, 0, v1, vcc
	v_add_co_u32_e32 v48, vcc, 0x18000, v0
	s_nop 1
	v_addc_co_u32_e32 v49, vcc, 0, v1, vcc
	v_add_co_u32_e32 v50, vcc, 0x1e000, v0
	s_nop 1
	v_addc_co_u32_e32 v51, vcc, 0, v1, vcc
	v_add_co_u32_e32 v52, vcc, 0x24000, v0
	s_nop 1
	v_addc_co_u32_e32 v53, vcc, 0, v1, vcc
	v_add_co_u32_e32 v54, vcc, 0x2a000, v0
	s_nop 1
	v_addc_co_u32_e32 v55, vcc, 0, v1, vcc
	global_load_dword v27, v[0:1], off nt
	global_load_dword v44, v[2:3], off offset:128 nt
	global_load_dword v45, v[4:5], off offset:256 nt
	global_load_dword v46, v[6:7], off offset:384 nt
	global_load_dword v47, v[48:49], off offset:512 nt
	s_nop 0
	global_load_dword v48, v[50:51], off offset:640 nt
	global_load_dword v49, v[52:53], off offset:768 nt
	s_nop 0
	global_load_dword v50, v[54:55], off offset:896 nt
	v_add_co_u32_e32 v2, vcc, 0x30000, v0
	s_nop 1
	v_addc_co_u32_e32 v3, vcc, 0, v1, vcc
	v_add_co_u32_e32 v4, vcc, 0x36000, v0
	s_nop 1
	v_addc_co_u32_e32 v5, vcc, 0, v1, vcc
	v_add_co_u32_e32 v6, vcc, 0x3c000, v0
	s_nop 1
	v_addc_co_u32_e32 v7, vcc, 0, v1, vcc
	v_add_co_u32_e32 v54, vcc, 0x42000, v0
	s_nop 1
	v_addc_co_u32_e32 v55, vcc, 0, v1, vcc
	v_add_co_u32_e32 v56, vcc, 0x48000, v0
	s_nop 1
	v_addc_co_u32_e32 v57, vcc, 0, v1, vcc
	v_add_co_u32_e32 v58, vcc, 0x4e000, v0
	s_nop 1
	v_addc_co_u32_e32 v59, vcc, 0, v1, vcc
	v_add_co_u32_e32 v60, vcc, 0x54000, v0
	s_nop 1
	v_addc_co_u32_e32 v61, vcc, 0, v1, vcc
	v_add_co_u32_e32 v62, vcc, 0x5a000, v0
	s_nop 1
	v_addc_co_u32_e32 v63, vcc, 0, v1, vcc
	global_load_dword v51, v[2:3], off offset:1024 nt
	global_load_dword v52, v[4:5], off offset:1152 nt
	global_load_dword v53, v[6:7], off offset:1280 nt
	s_nop 0
	global_load_dword v54, v[54:55], off offset:1408 nt
	s_nop 0
	global_load_dword v55, v[56:57], off offset:1536 nt
	s_nop 0
	global_load_dword v56, v[58:59], off offset:1664 nt
	global_load_dword v57, v[60:61], off offset:1792 nt
	s_nop 0
	global_load_dword v58, v[62:63], off offset:1920 nt
	v_add_co_u32_e32 v2, vcc, 0x60000, v0
	s_nop 1
	v_addc_co_u32_e32 v3, vcc, 0, v1, vcc
	v_add_co_u32_e32 v4, vcc, 0x66000, v0
	s_nop 1
	v_addc_co_u32_e32 v5, vcc, 0, v1, vcc
	v_add_co_u32_e32 v6, vcc, 0x6c000, v0
	s_nop 1
	v_addc_co_u32_e32 v7, vcc, 0, v1, vcc
	v_add_co_u32_e32 v62, vcc, 0x72000, v0
	s_nop 1
	v_addc_co_u32_e32 v63, vcc, 0, v1, vcc
	v_add_co_u32_e32 v64, vcc, 0x78000, v0
	s_nop 1
	v_addc_co_u32_e32 v65, vcc, 0, v1, vcc
	v_add_co_u32_e32 v66, vcc, 0x7e000, v0
	s_nop 1
	v_addc_co_u32_e32 v67, vcc, 0, v1, vcc
	v_add_co_u32_e32 v68, vcc, s48, v0
	s_nop 1
	v_addc_co_u32_e32 v69, vcc, 0, v1, vcc
	v_add_co_u32_e32 v70, vcc, 0x8a000, v0
	s_nop 1
	v_addc_co_u32_e32 v71, vcc, 0, v1, vcc
	global_load_dword v59, v[2:3], off offset:2048 nt
	global_load_dword v60, v[4:5], off offset:2176 nt
	global_load_dword v61, v[6:7], off offset:2304 nt
	s_nop 0
	global_load_dword v62, v[62:63], off offset:2432 nt
	s_nop 0
	global_load_dword v63, v[64:65], off offset:2560 nt
	s_nop 0
	global_load_dword v64, v[66:67], off offset:2688 nt
	global_load_dword v65, v[68:69], off offset:2816 nt
	s_nop 0
	global_load_dword v66, v[70:71], off offset:2944 nt
	v_add_co_u32_e32 v2, vcc, 0x90000, v0
	s_nop 1
	v_addc_co_u32_e32 v3, vcc, 0, v1, vcc
	v_add_co_u32_e32 v4, vcc, 0x96000, v0
	s_nop 1
	v_addc_co_u32_e32 v5, vcc, 0, v1, vcc
	v_add_co_u32_e32 v6, vcc, 0x9c000, v0
	s_nop 1
	v_addc_co_u32_e32 v7, vcc, 0, v1, vcc
	v_add_co_u32_e32 v70, vcc, 0xa2000, v0
	s_nop 1
	v_addc_co_u32_e32 v71, vcc, 0, v1, vcc
	v_add_co_u32_e32 v72, vcc, 0xa8000, v0
	s_nop 1
	v_addc_co_u32_e32 v73, vcc, 0, v1, vcc
	v_add_co_u32_e32 v74, vcc, 0xae000, v0
	s_nop 1
	v_addc_co_u32_e32 v75, vcc, 0, v1, vcc
	v_add_co_u32_e32 v76, vcc, 0xb4000, v0
	s_nop 1
	v_addc_co_u32_e32 v77, vcc, 0, v1, vcc
	v_add_co_u32_e32 v0, vcc, 0xba000, v0
	s_nop 1
	v_addc_co_u32_e32 v1, vcc, 0, v1, vcc
	global_load_dword v67, v[2:3], off offset:3072 nt
	global_load_dword v68, v[4:5], off offset:3200 nt
	global_load_dword v69, v[6:7], off offset:3328 nt
	s_nop 0
	global_load_dword v70, v[70:71], off offset:3456 nt
	s_nop 0
	global_load_dword v71, v[72:73], off offset:3584 nt
	s_nop 0
	global_load_dword v72, v[74:75], off offset:3712 nt
	global_load_dword v73, v[76:77], off offset:3840 nt
	s_nop 0
	global_load_dword v74, v[0:1], off offset:3968 nt
	s_andn2_b64 vcc, exec, s[0:1]
	s_cbranch_vccnz .LBB0_53
	v_lshl_add_u64 v[4:5], s[6:7], 2, v[22:23]
	global_load_dwordx4 v[0:3], v[4:5], off offset:16 nt
	s_nop 0
	global_load_dwordx4 v[4:7], v[4:5], off nt
	s_branch .LBB0_54

.LBB0_56:
	s_andn2_b64 vcc, exec, s[16:17]
	s_cbranch_vccnz .LBB0_58
	s_and_b32 s6, s40, 0x3fc0
	s_add_i32 s16, s6, 0xffffdc00
	v_or_b32_e32 v0, s16, v30
	v_mov_b32_e32 v1, v9
	s_and_b32 s26, s38, 0x3e0
	v_lshlrev_b64 v[0:1], 12, v[0:1]
	v_lshl_add_u64 v[0:1], s[10:11], 0, v[0:1]
	s_lshl_b32 s6, s26, 2
	v_lshl_add_u64 v[0:1], v[0:1], 0, s[6:7]
	v_lshl_add_u64 v[0:1], v[0:1], 0, v[8:9]
	v_add_co_u32_e32 v2, vcc, 0x2000, v0
	s_mov_b32 s17, s7
	s_nop 0
	v_addc_co_u32_e32 v3, vcc, 0, v1, vcc
	v_add_co_u32_e32 v4, vcc, 0x4000, v0
	s_nop 1
	v_addc_co_u32_e32 v5, vcc, 0, v1, vcc
	v_add_co_u32_e32 v6, vcc, 0x6000, v0
	s_nop 1
	v_addc_co_u32_e32 v7, vcc, 0, v1, vcc
	v_add_co_u32_e32 v44, vcc, 0x8000, v0
	s_nop 1
	v_addc_co_u32_e32 v45, vcc, 0, v1, vcc
	v_add_co_u32_e32 v46, vcc, 0xa000, v0
	s_nop 1
	v_addc_co_u32_e32 v47, vcc, 0, v1, vcc
	v_add_co_u32_e32 v48, vcc, 0xc000, v0
	s_nop 1
	v_addc_co_u32_e32 v49, vcc, 0, v1, vcc
	v_add_co_u32_e32 v50, vcc, 0xe000, v0
	s_nop 1
	v_addc_co_u32_e32 v51, vcc, 0, v1, vcc
	global_load_dword v27, v[0:1], off nt
	global_load_dword v54, v[2:3], off nt
	global_load_dword v55, v[4:5], off nt
	global_load_dword v56, v[6:7], off nt
	global_load_dword v57, v[44:45], off nt
	global_load_dword v58, v[46:47], off nt
	global_load_dword v59, v[48:49], off nt
	global_load_dword v60, v[50:51], off nt
	v_add_co_u32_e32 v2, vcc, 0x10000, v0
	s_nop 1
	v_addc_co_u32_e32 v3, vcc, 0, v1, vcc
	v_add_co_u32_e32 v4, vcc, 0x12000, v0
	s_nop 1
	v_addc_co_u32_e32 v5, vcc, 0, v1, vcc
	v_add_co_u32_e32 v6, vcc, 0x14000, v0
	s_nop 1
	v_addc_co_u32_e32 v7, vcc, 0, v1, vcc
	v_add_co_u32_e32 v44, vcc, 0x16000, v0
	s_nop 1
	v_addc_co_u32_e32 v45, vcc, 0, v1, vcc
	v_add_co_u32_e32 v46, vcc, 0x18000, v0
	s_nop 1
	v_addc_co_u32_e32 v47, vcc, 0, v1, vcc
	v_add_co_u32_e32 v48, vcc, 0x1a000, v0
	s_nop 1
	v_addc_co_u32_e32 v49, vcc, 0, v1, vcc
	v_add_co_u32_e32 v50, vcc, 0x1c000, v0
	s_nop 1
	v_addc_co_u32_e32 v51, vcc, 0, v1, vcc
	v_add_co_u32_e32 v52, vcc, 0x1e000, v0
	s_nop 1
	v_addc_co_u32_e32 v53, vcc, 0, v1, vcc
	global_load_dword v61, v[2:3], off nt
	global_load_dword v62, v[4:5], off nt
	global_load_dword v63, v[6:7], off nt
	global_load_dword v64, v[44:45], off nt
	global_load_dword v65, v[46:47], off nt
	global_load_dword v66, v[48:49], off nt
	global_load_dword v67, v[50:51], off nt
	global_load_dword v68, v[52:53], off nt
	v_add_co_u32_e32 v2, vcc, 0x20000, v0
	s_nop 1
	v_addc_co_u32_e32 v3, vcc, 0, v1, vcc
	v_add_co_u32_e32 v4, vcc, 0x22000, v0
	s_nop 1
	v_addc_co_u32_e32 v5, vcc, 0, v1, vcc
	v_add_co_u32_e32 v6, vcc, 0x24000, v0
	s_nop 1
	v_addc_co_u32_e32 v7, vcc, 0, v1, vcc
	v_add_co_u32_e32 v44, vcc, 0x26000, v0
	s_nop 1
	v_addc_co_u32_e32 v45, vcc, 0, v1, vcc
	v_add_co_u32_e32 v46, vcc, 0x28000, v0
	s_nop 1
	v_addc_co_u32_e32 v47, vcc, 0, v1, vcc
	v_add_co_u32_e32 v48, vcc, 0x2a000, v0
	s_nop 1
	v_addc_co_u32_e32 v49, vcc, 0, v1, vcc
	v_add_co_u32_e32 v50, vcc, 0x2c000, v0
	s_nop 1
	v_addc_co_u32_e32 v51, vcc, 0, v1, vcc
	v_add_co_u32_e32 v52, vcc, 0x2e000, v0
	s_nop 1
	v_addc_co_u32_e32 v53, vcc, 0, v1, vcc
	global_load_dword v69, v[2:3], off nt
	global_load_dword v70, v[4:5], off nt
	global_load_dword v71, v[6:7], off nt
	global_load_dword v72, v[44:45], off nt
	global_load_dword v73, v[46:47], off nt
	global_load_dword v74, v[48:49], off nt
	global_load_dword v75, v[50:51], off nt
	s_nop 0
	global_load_dword v52, v[52:53], off nt
	v_add_co_u32_e32 v2, vcc, 0x30000, v0
	s_nop 1
	v_addc_co_u32_e32 v3, vcc, 0, v1, vcc
	v_add_co_u32_e32 v4, vcc, 0x32000, v0
	s_nop 1
	v_addc_co_u32_e32 v5, vcc, 0, v1, vcc
	v_add_co_u32_e32 v6, vcc, 0x34000, v0
	s_nop 1
	v_addc_co_u32_e32 v7, vcc, 0, v1, vcc
	v_add_co_u32_e32 v44, vcc, 0x36000, v0
	s_nop 1
	v_addc_co_u32_e32 v45, vcc, 0, v1, vcc
	v_add_co_u32_e32 v46, vcc, 0x38000, v0
	s_nop 1
	v_addc_co_u32_e32 v47, vcc, 0, v1, vcc
	v_add_co_u32_e32 v48, vcc, 0x3a000, v0
	s_nop 1
	v_addc_co_u32_e32 v49, vcc, 0, v1, vcc
	v_add_co_u32_e32 v50, vcc, 0x3c000, v0
	s_nop 1
	v_addc_co_u32_e32 v51, vcc, 0, v1, vcc
	v_add_co_u32_e32 v0, vcc, 0x3e000, v0
	s_nop 1
	v_addc_co_u32_e32 v1, vcc, 0, v1, vcc
	global_load_dword v2, v[2:3], off nt
	s_nop 0
	global_load_dword v3, v[4:5], off nt
	s_nop 0
	global_load_dword v4, v[6:7], off nt
	global_load_dword v5, v[44:45], off nt
	s_nop 0
	global_load_dword v6, v[46:47], off nt
	global_load_dword v7, v[48:49], off nt
	global_load_dword v44, v[50:51], off nt
	s_nop 0
	global_load_dword v0, v[0:1], off nt
	s_waitcnt vmcnt(16)
	s_waitcnt vmcnt(0)
	ds_write2_b32 v31, v27, v54 offset1:66
	ds_write2_b32 v31, v55, v56 offset0:132 offset1:198
	ds_write2_b32 v37, v57, v58 offset0:8 offset1:74
	ds_write2_b32 v37, v59, v60 offset0:140 offset1:206
	ds_write2_b32 v38, v61, v62 offset0:16 offset1:82
	ds_write2_b32 v38, v63, v64 offset0:148 offset1:214
	ds_write2_b32 v39, v65, v66 offset0:24 offset1:90
	ds_write2_b32 v39, v67, v68 offset0:156 offset1:222
	ds_write2_b32 v40, v69, v70 offset0:32 offset1:98
	ds_write2_b32 v40, v71, v72 offset0:164 offset1:230
	ds_write2_b32 v41, v73, v74 offset0:40 offset1:106
	ds_write2_b32 v41, v75, v52 offset0:172 offset1:238
	ds_write2_b32 v42, v2, v3 offset0:48 offset1:114
	ds_write2_b32 v42, v4, v5 offset0:180 offset1:246
	ds_write2_b32 v43, v6, v7 offset0:56 offset1:122
	ds_write2_b32 v43, v44, v0 offset0:188 offset1:254
	s_waitcnt lgkmcnt(0)
	ds_read2_b32 v[4:5], v33 offset0:33 offset1:41
	ds_read2_b32 v[6:7], v33 offset1:8
	ds_read2_b32 v[44:45], v33 offset0:66 offset1:74
	ds_read2_b32 v[46:47], v33 offset0:99 offset1:107
	ds_read2_b32 v[48:49], v33 offset0:132 offset1:140
	ds_read2_b32 v[50:51], v33 offset0:165 offset1:173
	ds_read2_b32 v[52:53], v33 offset0:198 offset1:206
	ds_read2_b32 v[54:55], v33 offset0:231 offset1:239
	s_waitcnt lgkmcnt(6)
	v_cvt_pk_bf16_f32 v0, v6, v4
	v_or_b32_e32 v4, s26, v32
	v_lshl_add_u64 v[56:57], s[16:17], 1, v[14:15]
	v_lshlrev_b32_e32 v58, 11, v4
	v_mov_b32_e32 v59, v9
	s_waitcnt lgkmcnt(4)
	v_cvt_pk_bf16_f32 v1, v44, v46
	s_waitcnt lgkmcnt(2)
	v_cvt_pk_bf16_f32 v2, v48, v50
	s_waitcnt lgkmcnt(0)
	v_cvt_pk_bf16_f32 v3, v52, v54
	v_lshl_add_u64 v[58:59], v[56:57], 0, v[58:59]
	global_store_dwordx4 v[58:59], v[0:3], off
	v_or_b32_e32 v4, s26, v34
	v_lshlrev_b32_e32 v4, 11, v4
	v_cvt_pk_bf16_f32 v0, v7, v5
	v_cvt_pk_bf16_f32 v1, v45, v47
	v_cvt_pk_bf16_f32 v2, v49, v51
	v_cvt_pk_bf16_f32 v3, v53, v55
	ds_read2_b32 v[6:7], v33 offset0:49 offset1:57
	ds_read2_b32 v[44:45], v33 offset0:16 offset1:24
	ds_read2_b32 v[46:47], v33 offset0:82 offset1:90
	ds_read2_b32 v[48:49], v33 offset0:115 offset1:123
	ds_read2_b32 v[50:51], v33 offset0:148 offset1:156
	ds_read2_b32 v[52:53], v33 offset0:181 offset1:189
	ds_read2_b32 v[54:55], v33 offset0:214 offset1:222
	ds_read2_b32 v[58:59], v33 offset0:247 offset1:255
	v_mov_b32_e32 v5, v9
	v_lshl_add_u64 v[4:5], v[56:57], 0, v[4:5]
	global_store_dwordx4 v[4:5], v[0:3], off
	v_or_b32_e32 v4, s26, v35
	v_lshlrev_b32_e32 v4, 11, v4
	v_mov_b32_e32 v5, v9
	s_waitcnt lgkmcnt(6)
	v_cvt_pk_bf16_f32 v0, v44, v6
	s_waitcnt lgkmcnt(4)
	v_cvt_pk_bf16_f32 v1, v46, v48
	s_waitcnt lgkmcnt(2)
	v_cvt_pk_bf16_f32 v2, v50, v52
	s_waitcnt lgkmcnt(0)
	v_cvt_pk_bf16_f32 v3, v54, v58
	v_lshl_add_u64 v[4:5], v[56:57], 0, v[4:5]
	global_store_dwordx4 v[4:5], v[0:3], off
	v_or_b32_e32 v4, s26, v36
	v_lshlrev_b32_e32 v4, 11, v4
	v_mov_b32_e32 v5, v9
	v_cvt_pk_bf16_f32 v0, v45, v7
	v_cvt_pk_bf16_f32 v1, v47, v49
	v_cvt_pk_bf16_f32 v2, v51, v53
	v_cvt_pk_bf16_f32 v3, v55, v59
	v_lshl_add_u64 v[4:5], v[56:57], 0, v[4:5]
	global_store_dwordx4 v[4:5], v[0:3], off
	s_waitcnt lgkmcnt(0)

.LBB0_59:
	s_andn2_b64 vcc, exec, s[16:17]
	s_cbranch_vccnz .LBB0_23
	s_mul_hi_i32 s6, s90, 0x38e38e39
	s_lshr_b32 s16, s6, 31
	s_ashr_i32 s6, s6, 6
	s_add_i32 s6, s6, s16
	s_lshl_b32 s26, s6, 6
	s_mulk_i32 s6, 0xdc00
	s_add_i32 s16, s38, s6
	v_or_b32_e32 v2, s26, v30
	v_mov_b64_e32 v[0:1], s[8:9]
	v_mad_i64_i32 v[0:1], s[72:73], v2, s69, v[0:1]
	s_ashr_i32 s17, s16, 31
	v_lshl_add_u64 v[0:1], s[16:17], 2, v[0:1]
	v_lshl_add_u64 v[0:1], v[0:1], 0, v[8:9]
	v_add_co_u32_e32 v2, vcc, s42, v0
	s_ashr_i32 s27, s26, 31
	s_nop 0
	v_addc_co_u32_e32 v3, vcc, 0, v1, vcc
	v_add_co_u32_e32 v4, vcc, s44, v0
	s_nop 1
	v_addc_co_u32_e32 v5, vcc, 0, v1, vcc
	v_add_co_u32_e32 v6, vcc, s46, v0
	s_nop 1
	v_addc_co_u32_e32 v7, vcc, 0, v1, vcc
	v_add_co_u32_e32 v48, vcc, s62, v0
	s_nop 1
	v_addc_co_u32_e32 v49, vcc, 0, v1, vcc
	v_add_co_u32_e32 v50, vcc, s63, v0
	s_nop 1
	v_addc_co_u32_e32 v51, vcc, 0, v1, vcc
	v_add_co_u32_e32 v52, vcc, s64, v0
	s_nop 1
	v_addc_co_u32_e32 v53, vcc, 0, v1, vcc
	v_add_co_u32_e32 v54, vcc, s65, v0
	s_nop 1
	v_addc_co_u32_e32 v55, vcc, 0, v1, vcc
	global_load_dword v27, v[0:1], off nt
	global_load_dword v44, v[2:3], off nt
	global_load_dword v45, v[4:5], off nt
	global_load_dword v46, v[6:7], off nt
	global_load_dword v47, v[48:49], off nt
	s_nop 0
	global_load_dword v48, v[50:51], off nt
	global_load_dword v49, v[52:53], off nt
	s_nop 0
	global_load_dword v50, v[54:55], off nt
	v_add_co_u32_e32 v2, vcc, s66, v0
	s_nop 1
	v_addc_co_u32_e32 v3, vcc, 0, v1, vcc
	v_add_co_u32_e32 v4, vcc, s67, v0
	s_nop 1
	v_addc_co_u32_e32 v5, vcc, 0, v1, vcc
	v_add_co_u32_e32 v6, vcc, s68, v0
	s_nop 1
	v_addc_co_u32_e32 v7, vcc, 0, v1, vcc
	v_add_co_u32_e32 v54, vcc, s50, v0
	s_nop 1
	v_addc_co_u32_e32 v55, vcc, 0, v1, vcc
	v_add_co_u32_e32 v56, vcc, s70, v0
	s_nop 1
	v_addc_co_u32_e32 v57, vcc, 0, v1, vcc
	v_add_co_u32_e32 v58, vcc, s71, v0
	s_nop 1
	v_addc_co_u32_e32 v59, vcc, 0, v1, vcc
	v_add_co_u32_e32 v60, vcc, s74, v0
	s_nop 1
	v_addc_co_u32_e32 v61, vcc, 0, v1, vcc
	v_add_co_u32_e32 v62, vcc, s75, v0
	s_nop 1
	v_addc_co_u32_e32 v63, vcc, 0, v1, vcc
	global_load_dword v51, v[2:3], off nt
	global_load_dword v52, v[4:5], off nt
	global_load_dword v53, v[6:7], off nt
	s_nop 0
	global_load_dword v54, v[54:55], off nt
	s_nop 0
	global_load_dword v55, v[56:57], off nt
	s_nop 0
	global_load_dword v56, v[58:59], off nt
	global_load_dword v57, v[60:61], off nt
	s_nop 0
	global_load_dword v58, v[62:63], off nt
	v_add_co_u32_e32 v2, vcc, s76, v0
	s_nop 1
	v_addc_co_u32_e32 v3, vcc, 0, v1, vcc
	v_add_co_u32_e32 v4, vcc, s77, v0
	s_nop 1
	v_addc_co_u32_e32 v5, vcc, 0, v1, vcc
	v_add_co_u32_e32 v6, vcc, s78, v0
	s_nop 1
	v_addc_co_u32_e32 v7, vcc, 0, v1, vcc
	v_add_co_u32_e32 v62, vcc, s79, v0
	s_nop 1
	v_addc_co_u32_e32 v63, vcc, 0, v1, vcc
	v_add_co_u32_e32 v64, vcc, s80, v0
	s_nop 1
	v_addc_co_u32_e32 v65, vcc, 0, v1, vcc
	v_add_co_u32_e32 v66, vcc, s81, v0
	s_nop 1
	v_addc_co_u32_e32 v67, vcc, 0, v1, vcc
	v_add_co_u32_e32 v68, vcc, s82, v0
	s_nop 1
	v_addc_co_u32_e32 v69, vcc, 0, v1, vcc
	v_add_co_u32_e32 v70, vcc, s83, v0
	s_nop 1
	v_addc_co_u32_e32 v71, vcc, 0, v1, vcc
	global_load_dword v59, v[2:3], off nt
	global_load_dword v60, v[4:5], off nt
	global_load_dword v61, v[6:7], off nt
	s_nop 0
	global_load_dword v62, v[62:63], off nt
	s_nop 0
	global_load_dword v63, v[64:65], off nt
	s_nop 0
	global_load_dword v64, v[66:67], off nt
	global_load_dword v65, v[68:69], off nt
	s_nop 0
	global_load_dword v66, v[70:71], off nt
	v_add_co_u32_e32 v2, vcc, s84, v0
	s_nop 1
	v_addc_co_u32_e32 v3, vcc, 0, v1, vcc
	v_add_co_u32_e32 v4, vcc, s85, v0
	s_nop 1
	v_addc_co_u32_e32 v5, vcc, 0, v1, vcc
	v_add_co_u32_e32 v6, vcc, s86, v0
	s_nop 1
	v_addc_co_u32_e32 v7, vcc, 0, v1, vcc
	v_add_co_u32_e32 v70, vcc, s87, v0
	s_nop 1
	v_addc_co_u32_e32 v71, vcc, 0, v1, vcc
	v_add_co_u32_e32 v72, vcc, s88, v0
	s_nop 1
	v_addc_co_u32_e32 v73, vcc, 0, v1, vcc
	v_add_co_u32_e32 v74, vcc, s89, v0
	s_nop 1
	v_addc_co_u32_e32 v75, vcc, 0, v1, vcc
	v_add_co_u32_e32 v76, vcc, 0x21c000, v0
	s_nop 1
	v_addc_co_u32_e32 v77, vcc, 0, v1, vcc
	v_add_co_u32_e32 v0, vcc, 0x22e000, v0
	s_nop 1
	v_addc_co_u32_e32 v1, vcc, 0, v1, vcc
	global_load_dword v67, v[2:3], off nt
	global_load_dword v68, v[4:5], off nt
	global_load_dword v69, v[6:7], off nt
	s_nop 0
	global_load_dword v70, v[70:71], off nt
	s_nop 0
	global_load_dword v71, v[72:73], off nt
	s_nop 0
	global_load_dword v72, v[74:75], off nt
	global_load_dword v73, v[76:77], off nt
	s_nop 0
	global_load_dword v74, v[0:1], off nt
	s_andn2_b64 vcc, exec, s[2:3]
	s_cbranch_vccz .LBB0_21
	v_mov_b32_e32 v0, 1.0
	v_mov_b32_e32 v1, v0
	v_mov_b32_e32 v2, v0
	v_mov_b32_e32 v3, v0
	v_mov_b32_e32 v4, v0
	v_mov_b32_e32 v5, v0
	v_mov_b32_e32 v6, v0
	v_mov_b32_e32 v7, v0
	s_branch .LBB0_22

.LBB0_66:
	v_ashrrev_i32_e32 v14, 10, v6
	v_and_b32_e32 v2, 0x3ff, v6
	v_ashrrev_i32_e32 v15, 31, v14
	v_mad_u64_u32 v[18:19], s[26:27], v2, s21, v[0:1]
	v_ashrrev_i32_e32 v16, 10, v7
	v_and_b32_e32 v5, 0x3ff, v7
	v_lshl_add_u64 v[18:19], v[14:15], 2, v[18:19]
	v_ashrrev_i32_e32 v17, 31, v16
	v_mad_u64_u32 v[20:21], s[26:27], v5, s21, v[0:1]
	v_add_co_u32_e32 v18, vcc, s22, v18
	v_lshl_add_u64 v[20:21], v[16:17], 2, v[20:21]
	s_nop 0
	v_addc_co_u32_e32 v19, vcc, 0, v19, vcc
	v_lshlrev_b32_e32 v13, 2, v2
	v_lshlrev_b32_e32 v24, 2, v5
	v_add_co_u32_e32 v20, vcc, s22, v20
	global_load_dword v22, v13, s[12:13] nt
	global_load_dword v23, v24, s[12:13] nt
	v_addc_co_u32_e32 v21, vcc, 0, v21, vcc
	global_load_dword v24, v[18:19], off nt
	global_load_dword v25, v[20:21], off nt
	v_lshlrev_b64 v[14:15], 11, v[14:15]
	v_add_u32_e32 v12, -2, v12
	v_lshlrev_b32_e32 v2, 1, v2
	v_lshl_add_u64 v[14:15], s[8:9], 0, v[14:15]
	v_cmp_eq_u32_e32 vcc, 0, v12
	v_lshlrev_b64 v[16:17], 11, v[16:17]
	v_lshl_add_u64 v[14:15], v[14:15], 0, v[2:3]
	s_or_b64 s[18:19], vcc, s[18:19]
	v_lshl_add_u64 v[16:17], s[8:9], 0, v[16:17]
	v_lshlrev_b32_e32 v2, 1, v5
	v_add_co_u32_e32 v14, vcc, s24, v14
	v_lshl_add_u64 v[16:17], v[16:17], 0, v[2:3]
	s_nop 0
	v_addc_co_u32_e32 v15, vcc, 0, v15, vcc
	v_add_u32_e32 v7, s20, v7
	v_add_u32_e32 v6, s1, v6
	v_add_co_u32_e32 v16, vcc, 0x400000, v16
	s_waitcnt vmcnt(0)
	v_pk_mul_f32 v[18:19], v[24:25], v[22:23]
	s_nop 0
	v_and_b32_sdwa v5, v18, v10 dst_sel:DWORD dst_unused:UNUSED_PAD src0_sel:WORD_1 src1_sel:DWORD
	v_and_b32_sdwa v2, v19, v10 dst_sel:DWORD dst_unused:UNUSED_PAD src0_sel:WORD_1 src1_sel:DWORD
	v_add3_u32 v5, v18, v5, s23
	v_addc_co_u32_e32 v17, vcc, 0, v17, vcc
	v_add3_u32 v2, v19, v2, s23
	global_store_short_d16_hi v[14:15], v5, off
	global_store_short_d16_hi v[16:17], v2, off
	s_andn2_b64 exec, exec, s[18:19]
	s_cbranch_execnz .LBB0_66
	s_or_b64 exec, exec, s[18:19]
	v_mad_u64_u32 v[0:1], s[18:19], v9, s0, v[4:5]
	v_cmp_ne_u32_e32 vcc, v8, v9
	s_orn2_b64 s[18:19], vcc, exec

.LBB0_71:
	v_ashrrev_i32_e32 v8, 10, v0
	v_and_b32_e32 v1, 0x3ff, v0
	v_ashrrev_i32_e32 v9, 31, v8
	v_mad_u64_u32 v[12:13], s[14:15], v1, s1, v[2:3]
	v_lshl_add_u64 v[12:13], v[8:9], 2, v[12:13]
	v_add_co_u32_e32 v12, vcc, 0x3000, v12
	v_lshlrev_b32_e32 v5, 2, v1
	s_nop 0
	v_addc_co_u32_e32 v13, vcc, 0, v13, vcc
	global_load_dword v5, v5, s[12:13] nt
	v_lshlrev_b64 v[8:9], 11, v[8:9]
	global_load_dword v10, v[12:13], off nt
	v_add_u32_e32 v0, s0, v0
	v_lshlrev_b32_e32 v6, 1, v1
	v_lshl_add_u64 v[8:9], s[8:9], 0, v[8:9]
	v_cmp_lt_i32_e32 vcc, s11, v0
	v_lshl_add_u64 v[8:9], v[8:9], 0, v[6:7]
	s_or_b64 s[2:3], vcc, s[2:3]
	v_add_co_u32_e32 v8, vcc, 0x400000, v8
	s_waitcnt vmcnt(0)
	v_mul_f32_e32 v1, v10, v5
	v_bfe_u32 v5, v1, 16, 1
	v_addc_co_u32_e32 v9, vcc, 0, v9, vcc
	v_add3_u32 v1, v1, v5, s10
	global_store_short_d16_hi v[8:9], v1, off
	s_andn2_b64 exec, exec, s[2:3]
	s_cbranch_execnz .LBB0_71

.LBB0_81:
	v_add_co_u32_e32 v0, vcc, 0xffffd000, v70
	s_and_b32 s4, s0, 0xfffff000
	s_nop 0
	v_addc_co_u32_e32 v1, vcc, -1, v71, vcc
	global_load_dwordx4 v[60:63], v[0:1], off offset:-3072 nt
	s_waitcnt lgkmcnt(3)
	global_load_dwordx4 v[56:59], v[0:1], off offset:-2048 nt
	s_waitcnt lgkmcnt(2)
	global_load_dwordx4 v[48:51], v[0:1], off offset:-1024 nt
	s_waitcnt lgkmcnt(0)
	global_load_dwordx4 v[44:47], v[0:1], off nt
	v_add_co_u32_e32 v0, vcc, 0xffffe000, v70
	s_ashr_i32 s5, s4, 31
	s_nop 0
	v_addc_co_u32_e32 v1, vcc, -1, v71, vcc
	global_load_dwordx4 v[40:43], v[0:1], off offset:-3072 nt
	global_load_dwordx4 v[36:39], v[0:1], off offset:-2048 nt
	global_load_dwordx4 v[32:35], v[0:1], off offset:-1024 nt
	global_load_dwordx4 v[28:31], v[0:1], off nt
	v_add_co_u32_e32 v72, vcc, 0xfffff000, v70
	s_waitcnt vmcnt(7)
	v_mul_f32_e32 v64, v61, v61
	v_addc_co_u32_e32 v73, vcc, -1, v71, vcc
	global_load_dwordx4 v[20:23], v[72:73], off offset:-3072 nt
	global_load_dwordx4 v[24:27], v[72:73], off offset:-2048 nt
	global_load_dwordx4 v[16:19], v[72:73], off offset:-1024 nt
	global_load_dwordx4 v[12:15], v[70:71], off offset:-4096 nt
	global_load_dwordx4 v[8:11], v[70:71], off offset:-3072 nt
	global_load_dwordx4 v[4:7], v[70:71], off offset:-2048 nt
	global_load_dwordx4 v[0:3], v[70:71], off offset:-1024 nt
	global_load_dwordx4 v[52:55], v[70:71], off nt
	v_mul_f32_e32 v73, v63, v63
	v_cvt_pk_bf16_f32 v72, v60, v61
	s_waitcnt vmcnt(14)
	v_mul_f32_e32 v61, v57, v57
	v_mul_f32_e32 v84, v59, v59
	s_waitcnt vmcnt(13)
	v_mul_f32_e32 v85, v49, v49
	v_mul_f32_e32 v86, v51, v51
	s_waitcnt vmcnt(12)
	v_mul_f32_e32 v87, v45, v45
	v_mul_f32_e32 v88, v47, v47
	v_fmac_f32_e32 v64, v60, v60
	v_fmac_f32_e32 v73, v62, v62
	v_fmac_f32_e32 v61, v56, v56
	v_fmac_f32_e32 v84, v58, v58
	v_fmac_f32_e32 v85, v48, v48
	v_fmac_f32_e32 v86, v50, v50
	v_fmac_f32_e32 v87, v44, v44
	v_fmac_f32_e32 v88, v46, v46
	s_waitcnt vmcnt(11)
	v_mul_f32_e32 v60, v41, v41
	v_mul_f32_e32 v89, v43, v43
	s_waitcnt vmcnt(10)
	v_mul_f32_e32 v90, v37, v37
	v_mul_f32_e32 v91, v39, v39
	v_add_f32_e32 v64, v64, v73
	v_add_f32_e32 v61, v61, v84
	v_add_f32_e32 v73, v85, v86
	v_add_f32_e32 v84, v87, v88
	v_fmac_f32_e32 v60, v40, v40
	v_fmac_f32_e32 v89, v42, v42
	v_fmac_f32_e32 v90, v36, v36
	v_fmac_f32_e32 v91, v38, v38
	v_add_f32_e32 v61, v64, v61
	v_add_f32_e32 v60, v60, v89
	v_add_f32_e32 v64, v90, v91
	v_add_f32_e32 v61, v61, v73
	v_add_f32_e32 v60, v60, v64
	v_add_f32_e32 v61, v61, v84
	s_waitcnt vmcnt(9)
	v_mul_f32_e32 v92, v33, v33
	v_mul_f32_e32 v93, v35, v35
	s_waitcnt vmcnt(8)
	v_mul_f32_e32 v94, v29, v29
	v_mul_f32_e32 v95, v31, v31
	v_fmac_f32_e32 v92, v32, v32
	v_fmac_f32_e32 v93, v34, v34
	v_fmac_f32_e32 v94, v28, v28
	v_fmac_f32_e32 v95, v30, v30
	v_add_f32_e32 v89, v92, v93
	v_add_f32_e32 v90, v94, v95
	v_add_f32_e32 v60, v60, v89
	v_add_f32_e32 v60, v60, v90
	s_waitcnt vmcnt(7)
	v_mul_f32_e32 v85, v21, v21
	v_mul_f32_e32 v86, v23, v23
	s_waitcnt vmcnt(6)
	v_mul_f32_e32 v87, v25, v25
	v_mul_f32_e32 v88, v27, v27
	v_fmac_f32_e32 v85, v20, v20
	v_fmac_f32_e32 v86, v22, v22
	v_fmac_f32_e32 v87, v24, v24
	v_fmac_f32_e32 v88, v26, v26
	v_add_f32_e32 v64, v85, v86
	v_add_f32_e32 v73, v87, v88
	v_add_f32_e32 v64, v64, v73
	s_waitcnt vmcnt(5)
	v_mul_f32_e32 v73, v17, v17
	v_mul_f32_e32 v84, v19, v19
	v_fmac_f32_e32 v73, v16, v16
	v_fmac_f32_e32 v84, v18, v18
	v_add_f32_e32 v73, v73, v84
	v_add_f32_e32 v64, v64, v73
	s_waitcnt vmcnt(4)
	v_mul_f32_e32 v73, v13, v13
	v_mul_f32_e32 v84, v15, v15
	v_fmac_f32_e32 v73, v12, v12
	v_fmac_f32_e32 v84, v14, v14
	v_add_f32_e32 v73, v73, v84
	v_add_f32_e32 v64, v64, v73
	s_waitcnt vmcnt(3)
	v_mul_f32_e32 v73, v9, v9
	v_mul_f32_e32 v84, v11, v11
	v_fmac_f32_e32 v73, v8, v8
	v_fmac_f32_e32 v84, v10, v10
	v_add_f32_e32 v73, v73, v84
	s_waitcnt vmcnt(2)
	v_mul_f32_e32 v84, v5, v5
	v_mul_f32_e32 v85, v7, v7
	v_fmac_f32_e32 v84, v4, v4
	v_fmac_f32_e32 v85, v6, v6
	v_add_f32_e32 v84, v84, v85
	v_add_f32_e32 v73, v73, v84
	s_waitcnt vmcnt(1)
	v_mul_f32_e32 v84, v1, v1
	v_mul_f32_e32 v85, v3, v3
	v_fmac_f32_e32 v84, v0, v0
	v_fmac_f32_e32 v85, v2, v2
	v_add_f32_e32 v84, v84, v85
	v_add_f32_e32 v73, v73, v84
	s_waitcnt vmcnt(0)
	v_mul_f32_e32 v84, v53, v53
	v_mul_f32_e32 v85, v55, v55
	v_fmac_f32_e32 v84, v52, v52
	v_fmac_f32_e32 v85, v54, v54
	v_add_f32_e32 v84, v84, v85
	v_add_f32_e32 v84, v73, v84
	ds_bpermute_b32 v85, v76, v61
	ds_bpermute_b32 v86, v76, v60
	ds_bpermute_b32 v87, v76, v64
	ds_bpermute_b32 v88, v76, v84
	v_cvt_pk_bf16_f32 v73, v62, v63
	s_waitcnt lgkmcnt(3)
	v_add_f32_e32 v61, v61, v85
	s_waitcnt lgkmcnt(2)
	v_add_f32_e32 v62, v60, v86
	s_waitcnt lgkmcnt(1)
	v_add_f32_e32 v63, v64, v87
	s_waitcnt lgkmcnt(0)
	v_add_f32_e32 v64, v84, v88
	ds_bpermute_b32 v84, v77, v61
	ds_bpermute_b32 v85, v77, v62
	ds_bpermute_b32 v86, v77, v63
	ds_bpermute_b32 v87, v77, v64
	v_cvt_pk_bf16_f32 v60, v56, v57
	s_waitcnt lgkmcnt(3)
	v_add_f32_e32 v56, v61, v84
	s_waitcnt lgkmcnt(2)
	v_add_f32_e32 v57, v62, v85
	s_waitcnt lgkmcnt(1)
	v_add_f32_e32 v62, v63, v86
	s_waitcnt lgkmcnt(0)
	v_add_f32_e32 v63, v64, v87
	ds_bpermute_b32 v64, v78, v56
	ds_bpermute_b32 v84, v78, v57
	ds_bpermute_b32 v85, v78, v62
	ds_bpermute_b32 v86, v78, v63
	v_cvt_pk_bf16_f32 v61, v58, v59
	s_waitcnt lgkmcnt(3)
	v_add_f32_e32 v56, v56, v64
	s_waitcnt lgkmcnt(2)
	v_add_f32_e32 v57, v57, v84
	s_waitcnt lgkmcnt(1)
	v_add_f32_e32 v59, v62, v85
	s_waitcnt lgkmcnt(0)
	v_add_f32_e32 v62, v63, v86
	ds_bpermute_b32 v63, v79, v56
	ds_bpermute_b32 v64, v79, v57
	ds_bpermute_b32 v84, v79, v59
	ds_bpermute_b32 v85, v79, v62
	v_cvt_pk_bf16_f32 v58, v48, v49
	s_waitcnt lgkmcnt(3)
	v_add_f32_e32 v48, v56, v63
	s_waitcnt lgkmcnt(2)
	v_add_f32_e32 v49, v57, v64
	s_waitcnt lgkmcnt(1)
	v_add_f32_e32 v57, v59, v84
	s_waitcnt lgkmcnt(0)
	v_add_f32_e32 v62, v62, v85
	ds_bpermute_b32 v56, v80, v48
	ds_bpermute_b32 v63, v80, v49
	ds_bpermute_b32 v64, v80, v57
	ds_bpermute_b32 v84, v80, v62
	v_cvt_pk_bf16_f32 v59, v50, v51
	s_waitcnt lgkmcnt(3)
	v_add_f32_e32 v56, v48, v56
	s_waitcnt lgkmcnt(2)
	v_add_f32_e32 v50, v49, v63
	s_waitcnt lgkmcnt(1)
	v_add_f32_e32 v49, v57, v64
	s_waitcnt lgkmcnt(0)
	v_add_f32_e32 v48, v62, v84
	v_cvt_pk_bf16_f32 v63, v46, v47
	ds_bpermute_b32 v57, v81, v56
	ds_bpermute_b32 v51, v81, v50
	ds_bpermute_b32 v47, v81, v49
	ds_bpermute_b32 v46, v81, v48
	v_add_co_u32_e32 v84, vcc, s1, v68
	v_cvt_pk_bf16_f32 v62, v44, v45
	s_nop 0
	v_addc_co_u32_e32 v85, vcc, -1, v69, vcc
	v_lshl_add_u64 v[44:45], s[4:5], 2, v[66:67]
	global_store_dwordx2 v[84:85], v[72:73], off offset:-3584
	global_store_dwordx2 v[84:85], v[60:61], off offset:-3072
	global_store_dwordx2 v[84:85], v[58:59], off offset:-2560
	global_store_dwordx2 v[84:85], v[62:63], off offset:-2048
	s_and_saveexec_b64 s[12:13], s[2:3]
	s_cbranch_execz .LBB0_83
	s_waitcnt lgkmcnt(3)
	v_add_f32_e32 v56, v56, v57
	v_fmamk_f32 v56, v56, 0x3a800000, v82
	v_mul_f32_e32 v57, 0x4f800000, v56
	v_cmp_gt_f32_e32 vcc, s7, v56
	s_nop 1
	v_cndmask_b32_e32 v56, v56, v57, vcc
	v_sqrt_f32_e32 v57, v56
	s_nop 0
	v_add_u32_e32 v58, -1, v57
	v_fma_f32 v60, -v58, v57, v56
	v_add_u32_e32 v59, 1, v57
	v_cmp_ge_f32_e64 s[4:5], 0, v60
	s_nop 1
	v_cndmask_b32_e64 v58, v57, v58, s[4:5]
	v_fma_f32 v57, -v59, v57, v56
	v_cmp_lt_f32_e64 s[4:5], 0, v57
	s_nop 1
	v_cndmask_b32_e64 v57, v58, v59, s[4:5]
	v_mul_f32_e32 v58, 0x37800000, v57
	v_cndmask_b32_e32 v57, v57, v58, vcc
	v_cmp_class_f32_e32 vcc, v56, v83
	s_nop 1
	v_cndmask_b32_e32 v56, v57, v56, vcc
	v_div_scale_f32 v57, s[4:5], v56, v56, 1.0
	v_rcp_f32_e32 v58, v57
	s_and_b32 s4, s0, 0xffc
	v_fma_f32 v59, -v57, v58, 1.0
	v_fmac_f32_e32 v58, v59, v58
	v_div_scale_f32 v59, vcc, 1.0, v56, 1.0
	v_mul_f32_e32 v60, v59, v58
	v_fma_f32 v61, -v57, v60, v59
	v_fmac_f32_e32 v60, v61, v58
	v_fma_f32 v57, -v57, v60, v59
	v_div_fmas_f32 v57, v57, v58, v60
	v_div_fixup_f32 v58, v57, v56, 1.0
	v_lshlrev_b32_e64 v56, v75, s0
	v_and_b32_e32 v56, 0xff0, v56
	v_lshrrev_b32_e64 v59, v74, s4
	v_lshlrev_b32_e32 v64, 2, v56
	v_lshl_add_u64 v[56:57], v[44:45], 0, v[64:65]
	v_lshlrev_b32_e32 v64, 2, v59
	v_lshl_add_u64 v[56:57], v[56:57], 0, v[64:65]
	global_store_dword v[56:57], v58, off
